# hoist the four per-item colmax loads in both int8 weight quantisation loops (one round trip per item instead of four, no store-ack waits)
# speedup vs baseline: 1.0069x; 1.0011x over previous
; #define LAS __attribute__((address_space(3)))
; __device__ __forceinline__ float ld_agent(const float* p) { return __hip_atomic_load(p, __ATOMIC_RELAXED, __HIP_MEMORY_SCOPE_AGENT); }
; __device__ __forceinline__ int item_d0(int n0, int mode) { if (mode != 1) return n0; const int up = n0 >= FF, jj = up ? n0 - FF : n0; return (jj >> 7) * 256 + up * 128 + (jj & 127); }
; template <int MODE, bool GAIN>
; __device__ __forceinline__ void item_loads(const float* W, int N, const float* gain, int item, int lane, float (&r)[32]) {
;     ...
;     for (int i = 0; i < 32; ++i) { const int kk = 2 * i + (lane >> 5); float v = W[(size_t)(k0 + kk) * N + n0 + (lane & 31)]; if (GAIN) v *= gain[k0 + kk]; r[i] = v; }
; template <int MODE>
; __device__ __forceinline__ void quant_finish(const float (&r)[32], int K, int N, unsigned char* W8, const float* colmax, float* swinv, LAS float* scr, int item, int lane) {
;     const int nblk = N / 32, kb = item / nblk, nb = item % nblk, k0 = 64 * kb, n0 = 32 * nb, d0 = item_d0(n0, MODE);
; #pragma unroll
;     for (int i = 0; i < 32; ++i) { const int kk = 2 * i + (lane >> 5); scr[kk * 33 + (lane & 31)] = r[i]; }
;     asm volatile("s_waitcnt lgkmcnt(0)" ::: "memory");
;     const int c = lane & 7;
; #pragma unroll
;     for (int j = 0; j < 4; ++j) { const int n = (lane >> 3) + 8 * j; const LAS float* sp = scr + (8 * c) * 33 + n;
;         const float cm = ld_agent(colmax + n0 + n), sc = cm > 0.f ? 127.f / cm : 0.f;
;         unsigned w0 = 0u, w1 = 0u;
; #pragma unroll
;         for (int e = 0; e < 4; ++e) { int q0 = (int)rintf(sp[e * 33] * sc), q1 = (int)rintf(sp[(e + 4) * 33] * sc);
;             q0 = q0 < -127 ? -127 : (q0 > 127 ? 127 : q0); q1 = q1 < -127 ? -127 : (q1 > 127 ? 127 : q1);
;             w0 |= ((unsigned)q0 & 0xffu) << (8 * e); w1 |= ((unsigned)q1 & 0xffu) << (8 * e); }
;         u32x2 o; o.x = w0; o.y = w1;
;         *(u32x2*)(W8 + (size_t)(d0 + n) * K + k0 + 8 * c) = o;
;         if (kb == 0 && c == 0) swinv[d0 + n] = cm * (1.f / 127.f); }
;     asm volatile("s_waitcnt lgkmcnt(0)" ::: "memory");
.LBB0_77:
	s_waitcnt vmcnt(62)
	v_mul_f32_e32 v40, v40, v41
	s_waitcnt vmcnt(54)
	v_mul_f32_e32 v41, v56, v42
	s_waitcnt vmcnt(53)
	v_mul_f32_e32 v42, v57, v43
	s_waitcnt vmcnt(52)
	v_mul_f32_e32 v43, v58, v44
	s_waitcnt vmcnt(51)
	v_mul_f32_e32 v44, v59, v45
	s_waitcnt vmcnt(50)
	v_mul_f32_e32 v45, v60, v53
	s_waitcnt vmcnt(49)
	v_mul_f32_e32 v54, v61, v54
	v_add_u32_e32 v53, 0x400, v51
	s_waitcnt vmcnt(48)
	v_mul_f32_e32 v55, v62, v55
	s_waitcnt vmcnt(46)
	v_mul_f32_e32 v56, v63, v64
	s_waitcnt vmcnt(38)
	v_mul_f32_e32 v57, v72, v65
	s_waitcnt vmcnt(37)
	v_mul_f32_e32 v58, v73, v66
	s_waitcnt vmcnt(36)
	v_mul_f32_e32 v59, v74, v67
	ds_write2_b32 v51, v40, v41 offset1:66
	ds_write2_b32 v51, v42, v43 offset0:132 offset1:198
	ds_write2_b32 v53, v44, v45 offset0:8 offset1:74
	ds_write2_b32 v53, v54, v55 offset0:140 offset1:206
	v_add_u32_e32 v54, 0x800, v51
	s_waitcnt vmcnt(35)
	v_mul_f32_e32 v60, v75, v68
	s_waitcnt vmcnt(34)
	v_mul_f32_e32 v61, v76, v69
	s_waitcnt vmcnt(33)
	v_mul_f32_e32 v62, v77, v70
	s_waitcnt vmcnt(30)
	v_mul_f32_e32 v64, v79, v80
	s_waitcnt vmcnt(22)
	v_mul_f32_e32 v65, v88, v81
	s_waitcnt vmcnt(19)
	v_mul_f32_e32 v68, v91, v84
	s_waitcnt vmcnt(18)
	v_mul_f32_e32 v69, v92, v85
	s_waitcnt vmcnt(7)
	v_mul_f32_e32 v72, v95, v103
	s_waitcnt vmcnt(6)
	v_mul_f32_e32 v73, v96, v104
	s_waitcnt vmcnt(3)
	v_mul_f32_e32 v76, v99, v107
	s_waitcnt vmcnt(2)
	v_mul_f32_e32 v77, v100, v108
	ds_write2_b32 v54, v56, v57 offset0:16 offset1:82
	ds_write2_b32 v54, v58, v59 offset0:148 offset1:214
	v_add_u32_e32 v55, 0xc00, v51
	v_add_u32_e32 v56, 0x1000, v51
	v_add_u32_e32 v57, 0x1400, v51
	v_add_u32_e32 v58, 0x1800, v51
	v_add_u32_e32 v59, 0x1c00, v51
	v_mul_f32_e32 v63, v78, v71
	v_mul_f32_e32 v66, v89, v82
	v_mul_f32_e32 v67, v90, v83
	v_mul_f32_e32 v70, v93, v86
	v_mul_f32_e32 v71, v94, v87
	v_mul_f32_e32 v74, v97, v105
	v_mul_f32_e32 v75, v98, v106
	s_waitcnt vmcnt(1)
	v_mul_f32_e32 v78, v101, v109
	s_waitcnt vmcnt(0)
	v_mul_f32_e32 v79, v102, v110
	ds_write2_b32 v55, v60, v61 offset0:24 offset1:90
	ds_write2_b32 v55, v62, v63 offset0:156 offset1:222
	ds_write2_b32 v56, v64, v65 offset0:32 offset1:98
	ds_write2_b32 v56, v66, v67 offset0:164 offset1:230
	ds_write2_b32 v57, v68, v69 offset0:40 offset1:106
	ds_write2_b32 v57, v70, v71 offset0:172 offset1:238
	ds_write2_b32 v58, v72, v73 offset0:48 offset1:114
	ds_write2_b32 v58, v74, v75 offset0:180 offset1:246
	ds_write2_b32 v59, v76, v77 offset0:56 offset1:122
	ds_write2_b32 v59, v78, v79 offset0:188 offset1:254
	s_waitcnt lgkmcnt(0)
	v_lshl_add_u64 v[42:43], s[14:15], 2, v[6:7]
	global_load_dword v60, v[42:43], off sc1
	global_load_dword v200, v[42:43], off offset:32 sc1
	global_load_dword v201, v[42:43], off offset:64 sc1
	global_load_dword v202, v[42:43], off offset:96 sc1
	s_mulk_i32 s13, 0xfea8
	s_add_i32 s15, s14, 0xffffea80
	s_add_i32 s13, s23, s13
	s_cmpk_gt_i32 s13, 0xab
	s_cselect_b32 s14, s15, s14
	s_cselect_b32 s15, 0x80, 0
	s_ashr_i32 s13, s12, 31
	s_lshl_b32 s26, s14, 1
	s_and_b32 s14, s14, 0x60
	v_lshl_add_u64 v[40:41], v[4:5], 0, s[12:13]
	s_or_b32 s12, s14, s15
	ds_read2_b32 v[44:45], v47 offset1:33
	ds_read2_b32 v[62:63], v47 offset0:132 offset1:165
	s_and_b32 s13, s26, 0xffffff00
	s_or_b32 s26, s12, s13
	s_add_i32 s27, s23, 0x157
	s_cmpk_lt_u32 s27, 0x2af
	s_cselect_b64 s[12:13], -1, 0
	s_and_b64 s[12:13], s[4:5], s[12:13]
	s_waitcnt vmcnt(0)
	v_div_scale_f32 v61, s[14:15], v60, v60, s20
	v_rcp_f32_e32 v64, v61
	v_div_scale_f32 v65, vcc, s20, v60, s20
	v_fma_f32 v66, -v61, v64, 1.0
	v_fmac_f32_e32 v64, v66, v64
	v_mul_f32_e32 v66, v65, v64
	v_fma_f32 v67, -v61, v66, v65
	v_fmac_f32_e32 v66, v67, v64
	v_fma_f32 v61, -v61, v66, v65
	v_div_fmas_f32 v61, v61, v64, v66
	v_div_fixup_f32 v61, v61, v60, s20
	v_cmp_lt_f32_e32 vcc, 0, v60
	s_nop 1
	v_cndmask_b32_e32 v61, 0, v61, vcc
	s_waitcnt lgkmcnt(1)
	v_mul_f32_e32 v44, v44, v61
	v_rndne_f32_e32 v44, v44
	v_cvt_i32_f32_e32 v44, v44
	s_waitcnt lgkmcnt(0)
	v_mul_f32_e32 v62, v62, v61
	v_mul_f32_e32 v45, v61, v45
	v_mul_f32_e32 v63, v61, v63
	v_rndne_f32_e32 v62, v62
	v_rndne_f32_e32 v45, v45
	v_cvt_i32_f32_e32 v62, v62
	v_cvt_i32_f32_e32 v45, v45
	v_med3_i32 v64, v44, s21, v52
	v_rndne_f32_e32 v44, v63
	v_cvt_i32_f32_e32 v63, v44
	v_med3_i32 v65, v62, s21, v52
	v_med3_i32 v62, v45, s21, v52
	ds_read2_b32 v[44:45], v47 offset0:66 offset1:99
	v_med3_i32 v66, v63, s21, v52
	v_lshlrev_b32_e32 v67, 8, v62
	ds_read2_b32 v[62:63], v47 offset0:198 offset1:231
	v_perm_b32 v64, v67, v64, s22
	s_waitcnt lgkmcnt(1)
	v_mul_f32_e32 v44, v61, v44
	v_rndne_f32_e32 v44, v44
	v_mul_f32_e32 v45, v61, v45
	s_waitcnt lgkmcnt(0)
	v_mul_f32_e32 v62, v61, v62
	v_cvt_i32_f32_e32 v44, v44
	v_rndne_f32_e32 v62, v62
	v_rndne_f32_e32 v45, v45
	v_mul_f32_e32 v61, v61, v63
	v_cvt_i32_f32_e32 v62, v62
	v_cvt_i32_f32_e32 v45, v45
	v_rndne_f32_e32 v61, v61
	v_cvt_i32_f32_e32 v61, v61
	v_med3_i32 v44, v44, s21, v52
	v_med3_i32 v62, v62, s21, v52
	v_lshlrev_b32_e32 v44, 16, v44
	v_med3_i32 v45, v45, s21, v52
	v_lshlrev_b32_e32 v66, 8, v66
	v_and_b32_e32 v44, 0xff0000, v44
	v_lshlrev_b32_e32 v62, 16, v62
	v_med3_i32 v61, v61, s21, v52
	v_lshlrev_b32_e32 v45, 24, v45
	v_perm_b32 v65, v66, v65, s22
	v_and_b32_e32 v63, 0xff0000, v62
	v_or3_b32 v62, v64, v44, v45
	v_lshlrev_b32_e32 v44, 24, v61
	v_or3_b32 v63, v65, v63, v44
	v_or_b32_e32 v44, s26, v46
	v_ashrrev_i32_e32 v45, 31, v44
	v_lshlrev_b64 v[64:65], 11, v[44:45]
	v_lshl_add_u64 v[64:65], v[40:41], 0, v[64:65]
	global_store_dwordx2 v[64:65], v[62:63], off
	s_and_saveexec_b64 s[14:15], s[12:13]
	s_cbranch_execz .LBB0_79
	v_mul_f32_e32 v60, 0x3c010204, v60
	v_lshl_add_u64 v[44:45], v[44:45], 2, s[10:11]
	global_store_dword v[44:45], v60, off
; #define LAS __attribute__((address_space(3)))
; __device__ __forceinline__ float ld_agent(const float* p) { return __hip_atomic_load(p, __ATOMIC_RELAXED, __HIP_MEMORY_SCOPE_AGENT); }
; template <int MODE>
; __device__ __forceinline__ void quant_finish(const float (&r)[32], int K, int N, unsigned char* W8, const float* colmax, float* swinv, LAS float* scr, int item, int lane) {
;     ...
;     for (int j = 0; j < 4; ++j) { const int n = (lane >> 3) + 8 * j; const LAS float* sp = scr + (8 * c) * 33 + n;
;         const float cm = ld_agent(colmax + n0 + n), sc = cm > 0.f ? 127.f / cm : 0.f;
;         unsigned w0 = 0u, w1 = 0u;
; #pragma unroll
;         for (int e = 0; e < 4; ++e) { int q0 = (int)rintf(sp[e * 33] * sc), q1 = (int)rintf(sp[(e + 4) * 33] * sc);
;             q0 = q0 < -127 ? -127 : (q0 > 127 ? 127 : q0); q1 = q1 < -127 ? -127 : (q1 > 127 ? 127 : q1);
;             w0 |= ((unsigned)q0 & 0xffu) << (8 * e); w1 |= ((unsigned)q1 & 0xffu) << (8 * e); }
;         u32x2 o; o.x = w0; o.y = w1;
;         *(u32x2*)(W8 + (size_t)(d0 + n) * K + k0 + 8 * c) = o;
;         if (kb == 0 && c == 0) swinv[d0 + n] = cm * (1.f / 127.f); }
.LBB0_79:
	s_or_b64 exec, exec, s[14:15]
	v_mov_b32_e32 v60, v200
	ds_read2_b32 v[62:63], v47 offset0:8 offset1:41
	ds_read2_b32 v[64:65], v47 offset0:140 offset1:173
	ds_read2_b32 v[66:67], v47 offset0:74 offset1:107
	ds_read2_b32 v[68:69], v47 offset0:206 offset1:239
	v_or_b32_e32 v44, s26, v48
	v_ashrrev_i32_e32 v45, 31, v44
	v_lshlrev_b64 v[70:71], 11, v[44:45]
	v_div_scale_f32 v61, s[14:15], v60, v60, s20
	v_rcp_f32_e32 v72, v61
	v_div_scale_f32 v73, vcc, s20, v60, s20
	v_fma_f32 v74, -v61, v72, 1.0
	v_fmac_f32_e32 v72, v74, v72
	v_mul_f32_e32 v74, v73, v72
	v_fma_f32 v75, -v61, v74, v73
	v_fmac_f32_e32 v74, v75, v72
	v_fma_f32 v61, -v61, v74, v73
	v_div_fmas_f32 v61, v61, v72, v74
	v_div_fixup_f32 v61, v61, v60, s20
	v_cmp_lt_f32_e32 vcc, 0, v60
	s_nop 1
	v_cndmask_b32_e32 v61, 0, v61, vcc
	s_waitcnt lgkmcnt(3)
	v_mul_f32_e32 v63, v61, v63
	s_waitcnt lgkmcnt(2)
	v_mul_f32_e32 v65, v61, v65
	s_waitcnt lgkmcnt(1)
	v_mul_f32_e32 v66, v61, v66
	s_waitcnt lgkmcnt(0)
	v_mul_f32_e32 v68, v61, v68
	v_mul_f32_e32 v62, v62, v61
	v_mul_f32_e32 v64, v64, v61
	v_mul_f32_e32 v67, v61, v67
	v_mul_f32_e32 v61, v61, v69
	v_rndne_f32_e32 v63, v63
	v_rndne_f32_e32 v65, v65
	v_rndne_f32_e32 v66, v66
	v_rndne_f32_e32 v68, v68
	v_rndne_f32_e32 v62, v62
	v_rndne_f32_e32 v64, v64
	v_rndne_f32_e32 v67, v67
	v_rndne_f32_e32 v61, v61
	v_cvt_i32_f32_e32 v63, v63
	v_cvt_i32_f32_e32 v65, v65
	v_cvt_i32_f32_e32 v66, v66
	v_cvt_i32_f32_e32 v68, v68
	v_cvt_i32_f32_e32 v62, v62
	v_cvt_i32_f32_e32 v64, v64
	v_cvt_i32_f32_e32 v67, v67
	v_cvt_i32_f32_e32 v61, v61
	v_med3_i32 v63, v63, s21, v52
	v_med3_i32 v65, v65, s21, v52
	v_med3_i32 v66, v66, s21, v52
	v_med3_i32 v68, v68, s21, v52
	v_med3_i32 v62, v62, s21, v52
	v_med3_i32 v64, v64, s21, v52
	v_med3_i32 v67, v67, s21, v52
	v_med3_i32 v61, v61, s21, v52
	v_lshlrev_b32_e32 v63, 8, v63
	v_lshlrev_b32_e32 v65, 8, v65
	v_lshlrev_b32_e32 v66, 16, v66
	v_lshlrev_b32_e32 v68, 16, v68
	v_lshlrev_b32_e32 v67, 24, v67
	v_lshlrev_b32_e32 v61, 24, v61
	v_perm_b32 v62, v63, v62, s22
	v_perm_b32 v63, v65, v64, s22
	v_and_b32_e32 v64, 0xff0000, v66
	v_and_b32_e32 v65, 0xff0000, v68
	v_or3_b32 v62, v62, v64, v67
	v_or3_b32 v63, v63, v65, v61
	v_lshl_add_u64 v[64:65], v[40:41], 0, v[70:71]
	global_store_dwordx2 v[64:65], v[62:63], off
	s_and_saveexec_b64 s[14:15], s[12:13]
	s_cbranch_execz .LBB0_81
	v_mul_f32_e32 v60, 0x3c010204, v60
	v_lshl_add_u64 v[44:45], v[44:45], 2, s[10:11]
	global_store_dword v[44:45], v60, off
.LBB0_81:
	s_or_b64 exec, exec, s[14:15]
	v_mov_b32_e32 v60, v201
	ds_read2_b32 v[62:63], v47 offset0:16 offset1:49
	ds_read2_b32 v[64:65], v47 offset0:148 offset1:181
	ds_read2_b32 v[66:67], v47 offset0:82 offset1:115
	ds_read2_b32 v[68:69], v47 offset0:214 offset1:247
	v_or_b32_e32 v44, s26, v49
	v_ashrrev_i32_e32 v45, 31, v44
	v_lshlrev_b64 v[70:71], 11, v[44:45]
	v_div_scale_f32 v61, s[14:15], v60, v60, s20
	v_rcp_f32_e32 v72, v61
	v_div_scale_f32 v73, vcc, s20, v60, s20
	v_fma_f32 v74, -v61, v72, 1.0
	v_fmac_f32_e32 v72, v74, v72
	v_mul_f32_e32 v74, v73, v72
	v_fma_f32 v75, -v61, v74, v73
	v_fmac_f32_e32 v74, v75, v72
	v_fma_f32 v61, -v61, v74, v73
	v_div_fmas_f32 v61, v61, v72, v74
	v_div_fixup_f32 v61, v61, v60, s20
	v_cmp_lt_f32_e32 vcc, 0, v60
	s_nop 1
	v_cndmask_b32_e32 v61, 0, v61, vcc
	s_waitcnt lgkmcnt(3)
	v_mul_f32_e32 v63, v61, v63
	s_waitcnt lgkmcnt(2)
	v_mul_f32_e32 v65, v61, v65
	s_waitcnt lgkmcnt(1)
	v_mul_f32_e32 v66, v61, v66
	s_waitcnt lgkmcnt(0)
	v_mul_f32_e32 v68, v61, v68
	v_mul_f32_e32 v62, v62, v61
	v_mul_f32_e32 v64, v64, v61
	v_mul_f32_e32 v67, v61, v67
	v_mul_f32_e32 v61, v61, v69
	v_rndne_f32_e32 v63, v63
	v_rndne_f32_e32 v65, v65
	v_rndne_f32_e32 v66, v66
	v_rndne_f32_e32 v68, v68
	v_rndne_f32_e32 v62, v62
	v_rndne_f32_e32 v64, v64
	v_rndne_f32_e32 v67, v67
	v_rndne_f32_e32 v61, v61
	v_cvt_i32_f32_e32 v63, v63
	v_cvt_i32_f32_e32 v65, v65
	v_cvt_i32_f32_e32 v66, v66
	v_cvt_i32_f32_e32 v68, v68
	v_cvt_i32_f32_e32 v62, v62
	v_cvt_i32_f32_e32 v64, v64
	v_cvt_i32_f32_e32 v67, v67
	v_cvt_i32_f32_e32 v61, v61
	v_med3_i32 v63, v63, s21, v52
	v_med3_i32 v65, v65, s21, v52
	v_med3_i32 v66, v66, s21, v52
	v_med3_i32 v68, v68, s21, v52
	v_med3_i32 v62, v62, s21, v52
	v_med3_i32 v64, v64, s21, v52
	v_med3_i32 v67, v67, s21, v52
	v_med3_i32 v61, v61, s21, v52
	v_lshlrev_b32_e32 v63, 8, v63
	v_lshlrev_b32_e32 v65, 8, v65
	v_lshlrev_b32_e32 v66, 16, v66
	v_lshlrev_b32_e32 v68, 16, v68
	v_lshlrev_b32_e32 v67, 24, v67
	v_lshlrev_b32_e32 v61, 24, v61
	v_perm_b32 v62, v63, v62, s22
	v_perm_b32 v63, v65, v64, s22
	v_and_b32_e32 v64, 0xff0000, v66
	v_and_b32_e32 v65, 0xff0000, v68
	v_or3_b32 v62, v62, v64, v67
	v_or3_b32 v63, v63, v65, v61
	v_lshl_add_u64 v[64:65], v[40:41], 0, v[70:71]
	global_store_dwordx2 v[64:65], v[62:63], off
	s_and_saveexec_b64 s[14:15], s[12:13]
	s_cbranch_execz .LBB0_83
	v_mul_f32_e32 v60, 0x3c010204, v60
	v_lshl_add_u64 v[44:45], v[44:45], 2, s[10:11]
	global_store_dword v[44:45], v60, off
; #define LAS __attribute__((address_space(3)))
; __device__ __forceinline__ float ld_agent(const float* p) { return __hip_atomic_load(p, __ATOMIC_RELAXED, __HIP_MEMORY_SCOPE_AGENT); }
; template <int MODE>
; __device__ __forceinline__ void quant_finish(const float (&r)[32], int K, int N, unsigned char* W8, const float* colmax, float* swinv, LAS float* scr, int item, int lane) {
;     ...
;     for (int j = 0; j < 4; ++j) { const int n = (lane >> 3) + 8 * j; const LAS float* sp = scr + (8 * c) * 33 + n;
;         const float cm = ld_agent(colmax + n0 + n), sc = cm > 0.f ? 127.f / cm : 0.f;
;         unsigned w0 = 0u, w1 = 0u;
; #pragma unroll
;         for (int e = 0; e < 4; ++e) { int q0 = (int)rintf(sp[e * 33] * sc), q1 = (int)rintf(sp[(e + 4) * 33] * sc);
;             q0 = q0 < -127 ? -127 : (q0 > 127 ? 127 : q0); q1 = q1 < -127 ? -127 : (q1 > 127 ? 127 : q1);
;             w0 |= ((unsigned)q0 & 0xffu) << (8 * e); w1 |= ((unsigned)q1 & 0xffu) << (8 * e); }
;         u32x2 o; o.x = w0; o.y = w1;
;         *(u32x2*)(W8 + (size_t)(d0 + n) * K + k0 + 8 * c) = o;
;         if (kb == 0 && c == 0) swinv[d0 + n] = cm * (1.f / 127.f); }
;     asm volatile("s_waitcnt lgkmcnt(0)" ::: "memory");
; __global__ void __launch_bounds__(512, 2) mk_fwd(Args args) {
;     ...
;         for (int it = gw; it < I_1A; it += 2 * NGW) {
;             const int itB = it + NGW; float ra[32], rb[32];
;             item_loads<1, true>(args.in[3], 2 * FF, args.in[2], it, lane, ra);
;             if (itB < I_1A) item_loads<1, true>(args.in[3], 2 * FF, args.in[2], itB, lane, rb);
;             quant_finish<1>(ra, DM, 2 * FF, (unsigned char*)W1A, colmax1, swinv1, scr, it, lane);
;             if (itB < I_1A) quant_finish<1>(rb, DM, 2 * FF, (unsigned char*)W1A, colmax1, swinv1, scr, itB, lane);
;         }
.LBB0_83:
	s_or_b64 exec, exec, s[14:15]
	v_mov_b32_e32 v44, v202
	ds_read2_b32 v[60:61], v47 offset0:24 offset1:57
	ds_read2_b32 v[62:63], v47 offset0:156 offset1:189
	ds_read2_b32 v[64:65], v47 offset0:90 offset1:123
	ds_read2_b32 v[66:67], v47 offset0:222 offset1:255
	v_or_b32_e32 v42, s26, v50
	v_ashrrev_i32_e32 v43, 31, v42
	v_lshlrev_b64 v[68:69], 11, v[42:43]
	v_lshl_add_u64 v[40:41], v[40:41], 0, v[68:69]
	v_div_scale_f32 v45, s[14:15], v44, v44, s20
	v_rcp_f32_e32 v70, v45
	v_div_scale_f32 v71, vcc, s20, v44, s20
	v_fma_f32 v72, -v45, v70, 1.0
	v_fmac_f32_e32 v70, v72, v70
	v_mul_f32_e32 v72, v71, v70
	v_fma_f32 v73, -v45, v72, v71
	v_fmac_f32_e32 v72, v73, v70
	v_fma_f32 v45, -v45, v72, v71
	v_div_fmas_f32 v45, v45, v70, v72
	v_div_fixup_f32 v45, v45, v44, s20
	v_cmp_lt_f32_e32 vcc, 0, v44
	s_nop 1
	v_cndmask_b32_e32 v45, 0, v45, vcc
	s_waitcnt lgkmcnt(3)
	v_mul_f32_e32 v61, v45, v61
	s_waitcnt lgkmcnt(2)
	v_mul_f32_e32 v63, v45, v63
	s_waitcnt lgkmcnt(1)
	v_mul_f32_e32 v64, v45, v64
	s_waitcnt lgkmcnt(0)
	v_mul_f32_e32 v66, v45, v66
	v_mul_f32_e32 v60, v60, v45
	v_mul_f32_e32 v62, v62, v45
	v_mul_f32_e32 v65, v45, v65
	v_mul_f32_e32 v45, v45, v67
	v_rndne_f32_e32 v61, v61
	v_rndne_f32_e32 v63, v63
	v_rndne_f32_e32 v64, v64
	v_rndne_f32_e32 v66, v66
	v_rndne_f32_e32 v60, v60
	v_rndne_f32_e32 v62, v62
	v_rndne_f32_e32 v65, v65
	v_rndne_f32_e32 v45, v45
	v_cvt_i32_f32_e32 v61, v61
	v_cvt_i32_f32_e32 v63, v63
	v_cvt_i32_f32_e32 v64, v64
	v_cvt_i32_f32_e32 v66, v66
	v_cvt_i32_f32_e32 v60, v60
	v_cvt_i32_f32_e32 v62, v62
	v_cvt_i32_f32_e32 v65, v65
	v_cvt_i32_f32_e32 v45, v45
	v_med3_i32 v61, v61, s21, v52
	v_med3_i32 v63, v63, s21, v52
	v_med3_i32 v64, v64, s21, v52
	v_med3_i32 v66, v66, s21, v52
	v_med3_i32 v60, v60, s21, v52
	v_med3_i32 v62, v62, s21, v52
	v_med3_i32 v65, v65, s21, v52
	v_med3_i32 v45, v45, s21, v52
	v_lshlrev_b32_e32 v61, 8, v61
	v_lshlrev_b32_e32 v63, 8, v63
	v_lshlrev_b32_e32 v64, 16, v64
	v_lshlrev_b32_e32 v66, 16, v66
	v_lshlrev_b32_e32 v65, 24, v65
	v_lshlrev_b32_e32 v45, 24, v45
	v_perm_b32 v60, v61, v60, s22
	v_perm_b32 v61, v63, v62, s22
	v_and_b32_e32 v62, 0xff0000, v64
	v_and_b32_e32 v63, 0xff0000, v66
	v_or3_b32 v60, v60, v62, v65
	v_or3_b32 v61, v61, v63, v45
	global_store_dwordx2 v[40:41], v[60:61], off
	s_and_saveexec_b64 s[14:15], s[12:13]
	s_cbranch_execz .LBB0_85
	v_mul_f32_e32 v44, 0x3c010204, v44
	v_lshl_add_u64 v[40:41], v[42:43], 2, s[10:11]
	global_store_dword v[40:41], v44, off
.LBB0_85:
	s_or_b64 exec, exec, s[14:15]
	s_waitcnt lgkmcnt(0)
	s_andn2_b64 vcc, exec, s[8:9]
	s_cbranch_vccnz .LBB0_74
	s_lshr_b32 s8, s25, 31
	s_ashr_i32 s9, s25, 6
	s_add_i32 s12, s9, s8
	s_mul_i32 s8, s12, 0x158
	s_sub_i32 s9, s24, s8
	s_lshl_b32 s8, s9, 5
	s_add_i32 s13, s8, 0xffffea80
	s_cmpk_gt_i32 s9, 0xab
	s_cselect_b32 s13, s13, s8
	s_cselect_b32 s14, 0x80, 0
	ds_write2_b32 v51, v8, v9 offset1:66
	ds_write2_b32 v51, v10, v11 offset0:132 offset1:198
	ds_write2_b32 v53, v12, v13 offset0:8 offset1:74
	ds_write2_b32 v53, v14, v15 offset0:140 offset1:206
	ds_write2_b32 v54, v16, v17 offset0:16 offset1:82
	ds_write2_b32 v54, v18, v19 offset0:148 offset1:214
	ds_write2_b32 v55, v20, v21 offset0:24 offset1:90
	ds_write2_b32 v55, v22, v23 offset0:156 offset1:222
	ds_write2_b32 v56, v24, v25 offset0:32 offset1:98
	ds_write2_b32 v56, v26, v27 offset0:164 offset1:230
	ds_write2_b32 v57, v28, v29 offset0:40 offset1:106
	ds_write2_b32 v57, v30, v31 offset0:172 offset1:238
	ds_write2_b32 v58, v32, v33 offset0:48 offset1:114
	ds_write2_b32 v58, v34, v35 offset0:180 offset1:246
	ds_write2_b32 v59, v36, v37 offset0:56 offset1:122
	ds_write2_b32 v59, v38, v39 offset0:188 offset1:254
	s_ashr_i32 s9, s8, 31
	s_waitcnt lgkmcnt(0)
	v_lshl_add_u64 v[42:43], s[8:9], 2, v[6:7]
	global_load_dword v53, v[42:43], off sc1
	global_load_dword v200, v[42:43], off offset:32 sc1
	global_load_dword v201, v[42:43], off offset:64 sc1
	global_load_dword v202, v[42:43], off offset:96 sc1
	s_lshl_b32 s8, s12, 6
	s_lshl_b32 s12, s13, 1
	s_and_b32 s13, s13, 0x60
	s_or_b32 s13, s13, s14
	s_and_b32 s12, s12, 0xffffff00
	s_or_b32 s14, s13, s12
	ds_read2_b32 v[54:55], v47 offset1:33
	ds_read2_b32 v[56:57], v47 offset0:132 offset1:165
	ds_read2_b32 v[58:59], v47 offset0:66 offset1:99
	ds_read2_b32 v[60:61], v47 offset0:198 offset1:231
	s_addk_i32 s24, 0x157
	s_ashr_i32 s9, s8, 31
	v_or_b32_e32 v44, s14, v46
	s_cmpk_lt_u32 s24, 0x2af
	v_ashrrev_i32_e32 v45, 31, v44
	v_lshl_add_u64 v[40:41], v[4:5], 0, s[8:9]
	s_cselect_b64 s[8:9], -1, 0
	v_lshlrev_b64 v[62:63], 11, v[44:45]
	s_and_b64 s[8:9], s[4:5], s[8:9]
	s_waitcnt vmcnt(0)
	v_div_scale_f32 v64, s[12:13], v53, v53, s20
	v_rcp_f32_e32 v65, v64
	v_div_scale_f32 v66, vcc, s20, v53, s20
	v_fma_f32 v67, -v64, v65, 1.0
	v_fmac_f32_e32 v65, v67, v65
	v_mul_f32_e32 v67, v66, v65
	v_fma_f32 v68, -v64, v67, v66
	v_fmac_f32_e32 v67, v68, v65
	v_fma_f32 v64, -v64, v67, v66
	v_div_fmas_f32 v64, v64, v65, v67
	v_div_fixup_f32 v64, v64, v53, s20
	v_cmp_lt_f32_e32 vcc, 0, v53
	s_nop 1
	v_cndmask_b32_e32 v64, 0, v64, vcc
	s_waitcnt lgkmcnt(3)
	v_mul_f32_e32 v55, v64, v55
	s_waitcnt lgkmcnt(2)
	v_mul_f32_e32 v57, v64, v57
	s_waitcnt lgkmcnt(1)
	v_mul_f32_e32 v58, v64, v58
	s_waitcnt lgkmcnt(0)
	v_mul_f32_e32 v60, v64, v60
	v_mul_f32_e32 v54, v54, v64
	v_mul_f32_e32 v56, v56, v64
	v_mul_f32_e32 v59, v64, v59
	v_mul_f32_e32 v61, v64, v61
	v_rndne_f32_e32 v55, v55
	v_rndne_f32_e32 v57, v57
	v_rndne_f32_e32 v58, v58
	v_rndne_f32_e32 v60, v60
	v_rndne_f32_e32 v54, v54
	v_rndne_f32_e32 v56, v56
	v_rndne_f32_e32 v59, v59
	v_rndne_f32_e32 v61, v61
	v_cvt_i32_f32_e32 v55, v55
	v_cvt_i32_f32_e32 v57, v57
	v_cvt_i32_f32_e32 v58, v58
	v_cvt_i32_f32_e32 v60, v60
	v_cvt_i32_f32_e32 v54, v54
	v_cvt_i32_f32_e32 v56, v56
	v_cvt_i32_f32_e32 v59, v59
	v_cvt_i32_f32_e32 v61, v61
	v_med3_i32 v55, v55, s21, v52
	v_med3_i32 v57, v57, s21, v52
	v_med3_i32 v58, v58, s21, v52
	v_med3_i32 v60, v60, s21, v52
	v_med3_i32 v54, v54, s21, v52
	v_med3_i32 v56, v56, s21, v52
	v_med3_i32 v59, v59, s21, v52
	v_med3_i32 v61, v61, s21, v52
	v_lshlrev_b32_e32 v55, 8, v55
	v_lshlrev_b32_e32 v57, 8, v57
	v_lshlrev_b32_e32 v58, 16, v58
	v_lshlrev_b32_e32 v60, 16, v60
	v_lshlrev_b32_e32 v59, 24, v59
	v_lshlrev_b32_e32 v61, 24, v61
	v_perm_b32 v54, v55, v54, s22
	v_perm_b32 v55, v57, v56, s22
	v_and_b32_e32 v56, 0xff0000, v58
	v_and_b32_e32 v57, 0xff0000, v60
	v_or3_b32 v54, v54, v56, v59
	v_or3_b32 v55, v55, v57, v61
	v_lshl_add_u64 v[56:57], v[40:41], 0, v[62:63]
	global_store_dwordx2 v[56:57], v[54:55], off
	s_and_saveexec_b64 s[12:13], s[8:9]
	s_cbranch_execz .LBB0_88
	v_mul_f32_e32 v53, 0x3c010204, v53
	v_lshl_add_u64 v[44:45], v[44:45], 2, s[10:11]
	global_store_dword v[44:45], v53, off
; #define LAS __attribute__((address_space(3)))
; __device__ __forceinline__ float ld_agent(const float* p) { return __hip_atomic_load(p, __ATOMIC_RELAXED, __HIP_MEMORY_SCOPE_AGENT); }
; template <int MODE>
; __device__ __forceinline__ void quant_finish(const float (&r)[32], int K, int N, unsigned char* W8, const float* colmax, float* swinv, LAS float* scr, int item, int lane) {
;     ...
;     for (int j = 0; j < 4; ++j) { const int n = (lane >> 3) + 8 * j; const LAS float* sp = scr + (8 * c) * 33 + n;
;         const float cm = ld_agent(colmax + n0 + n), sc = cm > 0.f ? 127.f / cm : 0.f;
;         unsigned w0 = 0u, w1 = 0u;
; #pragma unroll
;         for (int e = 0; e < 4; ++e) { int q0 = (int)rintf(sp[e * 33] * sc), q1 = (int)rintf(sp[(e + 4) * 33] * sc);
;             q0 = q0 < -127 ? -127 : (q0 > 127 ? 127 : q0); q1 = q1 < -127 ? -127 : (q1 > 127 ? 127 : q1);
;             w0 |= ((unsigned)q0 & 0xffu) << (8 * e); w1 |= ((unsigned)q1 & 0xffu) << (8 * e); }
;         u32x2 o; o.x = w0; o.y = w1;
;         *(u32x2*)(W8 + (size_t)(d0 + n) * K + k0 + 8 * c) = o;
;         if (kb == 0 && c == 0) swinv[d0 + n] = cm * (1.f / 127.f); }
.LBB0_88:
	s_or_b64 exec, exec, s[12:13]
	v_mov_b32_e32 v53, v200
	ds_read2_b32 v[54:55], v47 offset0:8 offset1:41
	ds_read2_b32 v[56:57], v47 offset0:140 offset1:173
	ds_read2_b32 v[58:59], v47 offset0:74 offset1:107
	ds_read2_b32 v[60:61], v47 offset0:206 offset1:239
	v_or_b32_e32 v44, s14, v48
	v_ashrrev_i32_e32 v45, 31, v44
	v_lshlrev_b64 v[62:63], 11, v[44:45]
	v_div_scale_f32 v64, s[12:13], v53, v53, s20
	v_rcp_f32_e32 v65, v64
	v_div_scale_f32 v66, vcc, s20, v53, s20
	v_fma_f32 v67, -v64, v65, 1.0
	v_fmac_f32_e32 v65, v67, v65
	v_mul_f32_e32 v67, v66, v65
	v_fma_f32 v68, -v64, v67, v66
	v_fmac_f32_e32 v67, v68, v65
	v_fma_f32 v64, -v64, v67, v66
	v_div_fmas_f32 v64, v64, v65, v67
	v_div_fixup_f32 v64, v64, v53, s20
	v_cmp_lt_f32_e32 vcc, 0, v53
	s_nop 1
	v_cndmask_b32_e32 v64, 0, v64, vcc
	s_waitcnt lgkmcnt(3)
	v_mul_f32_e32 v55, v64, v55
	s_waitcnt lgkmcnt(2)
	v_mul_f32_e32 v57, v64, v57
	s_waitcnt lgkmcnt(1)
	v_mul_f32_e32 v58, v64, v58
	s_waitcnt lgkmcnt(0)
	v_mul_f32_e32 v60, v64, v60
	v_mul_f32_e32 v54, v54, v64
	v_mul_f32_e32 v56, v56, v64
	v_mul_f32_e32 v59, v64, v59
	v_mul_f32_e32 v61, v64, v61
	v_rndne_f32_e32 v55, v55
	v_rndne_f32_e32 v57, v57
	v_rndne_f32_e32 v58, v58
	v_rndne_f32_e32 v60, v60
	v_rndne_f32_e32 v54, v54
	v_rndne_f32_e32 v56, v56
	v_rndne_f32_e32 v59, v59
	v_rndne_f32_e32 v61, v61
	v_cvt_i32_f32_e32 v55, v55
	v_cvt_i32_f32_e32 v57, v57
	v_cvt_i32_f32_e32 v58, v58
	v_cvt_i32_f32_e32 v60, v60
	v_cvt_i32_f32_e32 v54, v54
	v_cvt_i32_f32_e32 v56, v56
	v_cvt_i32_f32_e32 v59, v59
	v_cvt_i32_f32_e32 v61, v61
	v_med3_i32 v55, v55, s21, v52
	v_med3_i32 v57, v57, s21, v52
	v_med3_i32 v58, v58, s21, v52
	v_med3_i32 v60, v60, s21, v52
	v_med3_i32 v54, v54, s21, v52
	v_med3_i32 v56, v56, s21, v52
	v_med3_i32 v59, v59, s21, v52
	v_med3_i32 v61, v61, s21, v52
	v_lshlrev_b32_e32 v55, 8, v55
	v_lshlrev_b32_e32 v57, 8, v57
	v_lshlrev_b32_e32 v58, 16, v58
	v_lshlrev_b32_e32 v60, 16, v60
	v_lshlrev_b32_e32 v59, 24, v59
	v_lshlrev_b32_e32 v61, 24, v61
	v_perm_b32 v54, v55, v54, s22
	v_perm_b32 v55, v57, v56, s22
	v_and_b32_e32 v56, 0xff0000, v58
	v_and_b32_e32 v57, 0xff0000, v60
	v_or3_b32 v54, v54, v56, v59
	v_or3_b32 v55, v55, v57, v61
	v_lshl_add_u64 v[56:57], v[40:41], 0, v[62:63]
	global_store_dwordx2 v[56:57], v[54:55], off
	s_and_saveexec_b64 s[12:13], s[8:9]
	s_cbranch_execz .LBB0_90
	v_mul_f32_e32 v53, 0x3c010204, v53
	v_lshl_add_u64 v[44:45], v[44:45], 2, s[10:11]
	global_store_dword v[44:45], v53, off
.LBB0_90:
	s_or_b64 exec, exec, s[12:13]
	v_mov_b32_e32 v53, v201
	ds_read2_b32 v[54:55], v47 offset0:16 offset1:49
	ds_read2_b32 v[56:57], v47 offset0:148 offset1:181
	ds_read2_b32 v[58:59], v47 offset0:82 offset1:115
	ds_read2_b32 v[60:61], v47 offset0:214 offset1:247
	v_or_b32_e32 v44, s14, v49
	v_ashrrev_i32_e32 v45, 31, v44
	v_lshlrev_b64 v[62:63], 11, v[44:45]
	v_div_scale_f32 v64, s[12:13], v53, v53, s20
	v_rcp_f32_e32 v65, v64
	v_div_scale_f32 v66, vcc, s20, v53, s20
	v_fma_f32 v67, -v64, v65, 1.0
	v_fmac_f32_e32 v65, v67, v65
	v_mul_f32_e32 v67, v66, v65
	v_fma_f32 v68, -v64, v67, v66
	v_fmac_f32_e32 v67, v68, v65
	v_fma_f32 v64, -v64, v67, v66
	v_div_fmas_f32 v64, v64, v65, v67
	v_div_fixup_f32 v64, v64, v53, s20
	v_cmp_lt_f32_e32 vcc, 0, v53
	s_nop 1
	v_cndmask_b32_e32 v64, 0, v64, vcc
	s_waitcnt lgkmcnt(3)
	v_mul_f32_e32 v55, v64, v55
	s_waitcnt lgkmcnt(2)
	v_mul_f32_e32 v57, v64, v57
	s_waitcnt lgkmcnt(1)
	v_mul_f32_e32 v58, v64, v58
	s_waitcnt lgkmcnt(0)
	v_mul_f32_e32 v60, v64, v60
	v_mul_f32_e32 v54, v54, v64
	v_mul_f32_e32 v56, v56, v64
	v_mul_f32_e32 v59, v64, v59
	v_mul_f32_e32 v61, v64, v61
	v_rndne_f32_e32 v55, v55
	v_rndne_f32_e32 v57, v57
	v_rndne_f32_e32 v58, v58
	v_rndne_f32_e32 v60, v60
	v_rndne_f32_e32 v54, v54
	v_rndne_f32_e32 v56, v56
	v_rndne_f32_e32 v59, v59
	v_rndne_f32_e32 v61, v61
	v_cvt_i32_f32_e32 v55, v55
	v_cvt_i32_f32_e32 v57, v57
	v_cvt_i32_f32_e32 v58, v58
	v_cvt_i32_f32_e32 v60, v60
	v_cvt_i32_f32_e32 v54, v54
	v_cvt_i32_f32_e32 v56, v56
	v_cvt_i32_f32_e32 v59, v59
	v_cvt_i32_f32_e32 v61, v61
	v_med3_i32 v55, v55, s21, v52
	v_med3_i32 v57, v57, s21, v52
	v_med3_i32 v58, v58, s21, v52
	v_med3_i32 v60, v60, s21, v52
	v_med3_i32 v54, v54, s21, v52
	v_med3_i32 v56, v56, s21, v52
	v_med3_i32 v59, v59, s21, v52
	v_med3_i32 v61, v61, s21, v52
	v_lshlrev_b32_e32 v55, 8, v55
	v_lshlrev_b32_e32 v57, 8, v57
	v_lshlrev_b32_e32 v58, 16, v58
	v_lshlrev_b32_e32 v60, 16, v60
	v_lshlrev_b32_e32 v59, 24, v59
	v_lshlrev_b32_e32 v61, 24, v61
	v_perm_b32 v54, v55, v54, s22
	v_perm_b32 v55, v57, v56, s22
	v_and_b32_e32 v56, 0xff0000, v58
	v_and_b32_e32 v57, 0xff0000, v60
	v_or3_b32 v54, v54, v56, v59
	v_or3_b32 v55, v55, v57, v61
	v_lshl_add_u64 v[56:57], v[40:41], 0, v[62:63]
	global_store_dwordx2 v[56:57], v[54:55], off
	s_and_saveexec_b64 s[12:13], s[8:9]
	s_cbranch_execz .LBB0_92
	v_mul_f32_e32 v53, 0x3c010204, v53
	v_lshl_add_u64 v[44:45], v[44:45], 2, s[10:11]
	global_store_dword v[44:45], v53, off
; #define LAS __attribute__((address_space(3)))
; __device__ __forceinline__ float ld_agent(const float* p) { return __hip_atomic_load(p, __ATOMIC_RELAXED, __HIP_MEMORY_SCOPE_AGENT); }
; template <int MODE>
; __device__ __forceinline__ void quant_finish(const float (&r)[32], int K, int N, unsigned char* W8, const float* colmax, float* swinv, LAS float* scr, int item, int lane) {
;     ...
;     for (int j = 0; j < 4; ++j) { const int n = (lane >> 3) + 8 * j; const LAS float* sp = scr + (8 * c) * 33 + n;
;         const float cm = ld_agent(colmax + n0 + n), sc = cm > 0.f ? 127.f / cm : 0.f;
;         unsigned w0 = 0u, w1 = 0u;
; #pragma unroll
;         for (int e = 0; e < 4; ++e) { int q0 = (int)rintf(sp[e * 33] * sc), q1 = (int)rintf(sp[(e + 4) * 33] * sc);
;             q0 = q0 < -127 ? -127 : (q0 > 127 ? 127 : q0); q1 = q1 < -127 ? -127 : (q1 > 127 ? 127 : q1);
;             w0 |= ((unsigned)q0 & 0xffu) << (8 * e); w1 |= ((unsigned)q1 & 0xffu) << (8 * e); }
;         u32x2 o; o.x = w0; o.y = w1;
;         *(u32x2*)(W8 + (size_t)(d0 + n) * K + k0 + 8 * c) = o;
;         if (kb == 0 && c == 0) swinv[d0 + n] = cm * (1.f / 127.f); }
.LBB0_92:
	s_or_b64 exec, exec, s[12:13]
	v_mov_b32_e32 v44, v202
	ds_read2_b32 v[54:55], v47 offset0:24 offset1:57
	ds_read2_b32 v[56:57], v47 offset0:156 offset1:189
	ds_read2_b32 v[58:59], v47 offset0:90 offset1:123
	ds_read2_b32 v[60:61], v47 offset0:222 offset1:255
	v_or_b32_e32 v42, s14, v50
	v_ashrrev_i32_e32 v43, 31, v42
	v_lshlrev_b64 v[62:63], 11, v[42:43]
	v_lshl_add_u64 v[40:41], v[40:41], 0, v[62:63]
	v_div_scale_f32 v45, s[12:13], v44, v44, s20
	v_rcp_f32_e32 v53, v45
	v_div_scale_f32 v64, vcc, s20, v44, s20
	v_fma_f32 v65, -v45, v53, 1.0
	v_fmac_f32_e32 v53, v65, v53
	v_mul_f32_e32 v65, v64, v53
	v_fma_f32 v66, -v45, v65, v64
	v_fmac_f32_e32 v65, v66, v53
	v_fma_f32 v45, -v45, v65, v64
	v_div_fmas_f32 v45, v45, v53, v65
	v_div_fixup_f32 v45, v45, v44, s20
	v_cmp_lt_f32_e32 vcc, 0, v44
	s_nop 1
	v_cndmask_b32_e32 v45, 0, v45, vcc
	s_waitcnt lgkmcnt(3)
	v_mul_f32_e32 v53, v54, v45
	s_waitcnt lgkmcnt(2)
	v_mul_f32_e32 v54, v56, v45
	v_mul_f32_e32 v55, v45, v55
	v_mul_f32_e32 v56, v45, v57
	s_waitcnt lgkmcnt(1)
	v_mul_f32_e32 v57, v45, v58
	s_waitcnt lgkmcnt(0)
	v_mul_f32_e32 v58, v45, v60
	v_mul_f32_e32 v59, v45, v59
	v_mul_f32_e32 v45, v45, v61
	v_rndne_f32_e32 v55, v55
	v_rndne_f32_e32 v56, v56
	v_rndne_f32_e32 v57, v57
	v_rndne_f32_e32 v58, v58
	v_rndne_f32_e32 v53, v53
	v_rndne_f32_e32 v54, v54
	v_rndne_f32_e32 v59, v59
	v_rndne_f32_e32 v45, v45
	v_cvt_i32_f32_e32 v55, v55
	v_cvt_i32_f32_e32 v56, v56
	v_cvt_i32_f32_e32 v57, v57
	v_cvt_i32_f32_e32 v58, v58
	v_cvt_i32_f32_e32 v53, v53
	v_cvt_i32_f32_e32 v54, v54
	v_cvt_i32_f32_e32 v59, v59
	v_cvt_i32_f32_e32 v45, v45
	v_med3_i32 v55, v55, s21, v52
	v_med3_i32 v56, v56, s21, v52
	v_med3_i32 v57, v57, s21, v52
	v_med3_i32 v58, v58, s21, v52
	v_med3_i32 v53, v53, s21, v52
	v_med3_i32 v54, v54, s21, v52
	v_med3_i32 v59, v59, s21, v52
	v_med3_i32 v45, v45, s21, v52
	v_lshlrev_b32_e32 v55, 8, v55
	v_lshlrev_b32_e32 v56, 8, v56
	v_lshlrev_b32_e32 v57, 16, v57
	v_lshlrev_b32_e32 v58, 16, v58
	v_lshlrev_b32_e32 v59, 24, v59
	v_lshlrev_b32_e32 v45, 24, v45
	v_perm_b32 v53, v55, v53, s22
	v_perm_b32 v55, v56, v54, s22
	v_and_b32_e32 v54, 0xff0000, v57
	v_and_b32_e32 v56, 0xff0000, v58
	v_or3_b32 v54, v53, v54, v59
	v_or3_b32 v55, v55, v56, v45
	global_store_dwordx2 v[40:41], v[54:55], off
	s_and_saveexec_b64 s[12:13], s[8:9]
	s_cbranch_execz .LBB0_73
	v_mul_f32_e32 v44, 0x3c010204, v44
	v_lshl_add_u64 v[40:41], v[42:43], 2, s[10:11]
	global_store_dword v[40:41], v44, off
	s_branch .LBB0_73

; #define LAS __attribute__((address_space(3)))
; __device__ __forceinline__ float ld_agent(const float* p) { return __hip_atomic_load(p, __ATOMIC_RELAXED, __HIP_MEMORY_SCOPE_AGENT); }
; __device__ __forceinline__ int item_d0(int n0, int mode) { if (mode != 1) return n0; const int up = n0 >= FF, jj = up ? n0 - FF : n0; return (jj >> 7) * 256 + up * 128 + (jj & 127); }
; template <int MODE>
; __device__ __forceinline__ void quant_finish(const float (&r)[32], int K, int N, unsigned char* W8, const float* colmax, float* swinv, LAS float* scr, int item, int lane) {
;     const int nblk = N / 32, kb = item / nblk, nb = item % nblk, k0 = 64 * kb, n0 = 32 * nb, d0 = item_d0(n0, MODE);
; #pragma unroll
;     for (int i = 0; i < 32; ++i) { const int kk = 2 * i + (lane >> 5); scr[kk * 33 + (lane & 31)] = r[i]; }
;     asm volatile("s_waitcnt lgkmcnt(0)" ::: "memory");
;     const int c = lane & 7;
; #pragma unroll
;     for (int j = 0; j < 4; ++j) { const int n = (lane >> 3) + 8 * j; const LAS float* sp = scr + (8 * c) * 33 + n;
;         const float cm = ld_agent(colmax + n0 + n), sc = cm > 0.f ? 127.f / cm : 0.f;
;         unsigned w0 = 0u, w1 = 0u;
; #pragma unroll
;         for (int e = 0; e < 4; ++e) { int q0 = (int)rintf(sp[e * 33] * sc), q1 = (int)rintf(sp[(e + 4) * 33] * sc);
;             q0 = q0 < -127 ? -127 : (q0 > 127 ? 127 : q0); q1 = q1 < -127 ? -127 : (q1 > 127 ? 127 : q1);
;             w0 |= ((unsigned)q0 & 0xffu) << (8 * e); w1 |= ((unsigned)q1 & 0xffu) << (8 * e); }
;         u32x2 o; o.x = w0; o.y = w1;
;         *(u32x2*)(W8 + (size_t)(d0 + n) * K + k0 + 8 * c) = o;
;         if (kb == 0 && c == 0) swinv[d0 + n] = cm * (1.f / 127.f); }
;     asm volatile("s_waitcnt lgkmcnt(0)" ::: "memory");
.LBB0_134:
	s_waitcnt vmcnt(0)
	v_mul_f32_e32 v38, v38, v39
	v_mul_f32_e32 v39, v55, v40
	v_mul_f32_e32 v40, v56, v41
	v_mul_f32_e32 v41, v57, v42
	v_mul_f32_e32 v42, v58, v43
	v_mul_f32_e32 v43, v59, v44
	v_mul_f32_e32 v44, v60, v45
	v_mul_f32_e32 v45, v61, v54
	v_mul_f32_e32 v56, v62, v63
	v_mul_f32_e32 v57, v71, v64
	v_add_u32_e32 v54, 0x400, v52
	v_add_u32_e32 v55, 0x800, v52
	v_mul_f32_e32 v58, v72, v65
	v_mul_f32_e32 v59, v73, v66
	v_mul_f32_e32 v60, v74, v67
	v_mul_f32_e32 v61, v75, v68
	ds_write2_b32 v52, v38, v39 offset1:66
	ds_write2_b32 v52, v40, v41 offset0:132 offset1:198
	ds_write2_b32 v54, v42, v43 offset0:8 offset1:74
	ds_write2_b32 v54, v44, v45 offset0:140 offset1:206
	ds_write2_b32 v55, v56, v57 offset0:16 offset1:82
	ds_write2_b32 v55, v58, v59 offset0:148 offset1:214
	v_add_u32_e32 v56, 0xc00, v52
	v_mul_f32_e32 v62, v76, v69
	v_mul_f32_e32 v63, v77, v70
	v_mul_f32_e32 v64, v78, v79
	v_mul_f32_e32 v65, v87, v80
	v_mul_f32_e32 v68, v90, v83
	v_mul_f32_e32 v69, v91, v84
	v_mul_f32_e32 v72, v94, v102
	v_mul_f32_e32 v73, v95, v103
	v_mul_f32_e32 v76, v98, v106
	v_mul_f32_e32 v77, v99, v107
	ds_write2_b32 v56, v60, v61 offset0:24 offset1:90
	ds_write2_b32 v56, v62, v63 offset0:156 offset1:222
	v_add_u32_e32 v57, 0x1000, v52
	v_add_u32_e32 v58, 0x1400, v52
	v_add_u32_e32 v59, 0x1800, v52
	v_add_u32_e32 v60, 0x1c00, v52
	v_mul_f32_e32 v66, v88, v81
	v_mul_f32_e32 v67, v89, v82
	v_mul_f32_e32 v70, v92, v85
	v_mul_f32_e32 v71, v93, v86
	v_mul_f32_e32 v74, v96, v104
	v_mul_f32_e32 v75, v97, v105
	v_mul_f32_e32 v78, v100, v108
	v_mul_f32_e32 v79, v101, v109
	ds_write2_b32 v57, v64, v65 offset0:32 offset1:98
	ds_write2_b32 v57, v66, v67 offset0:164 offset1:230
	ds_write2_b32 v58, v68, v69 offset0:40 offset1:106
	ds_write2_b32 v58, v70, v71 offset0:172 offset1:238
	ds_write2_b32 v59, v72, v73 offset0:48 offset1:114
	ds_write2_b32 v59, v74, v75 offset0:180 offset1:246
	ds_write2_b32 v60, v76, v77 offset0:56 offset1:122
	ds_write2_b32 v60, v78, v79 offset0:188 offset1:254
	s_waitcnt lgkmcnt(0)
	v_lshl_add_u64 v[40:41], s[6:7], 2, v[4:5]
	global_load_dword v44, v[40:41], off sc1
	global_load_dword v200, v[40:41], off offset:32 sc1
	global_load_dword v201, v[40:41], off offset:64 sc1
	global_load_dword v202, v[40:41], off offset:96 sc1
	ds_read2_b32 v[42:43], v48 offset1:33
	ds_read2_b32 v[62:63], v48 offset0:132 offset1:165
	ds_read2_b32 v[64:65], v48 offset0:66 offset1:99
	ds_read2_b32 v[66:67], v48 offset0:198 offset1:231
	s_ashr_i32 s13, s12, 31
	s_add_i32 s7, s25, 0x10f
	s_cmpk_lt_u32 s7, 0x21f
	v_lshl_add_u64 v[38:39], v[2:3], 0, s[12:13]
	s_cselect_b64 s[12:13], -1, 0
	s_and_b64 s[12:13], s[0:1], s[12:13]
	s_waitcnt vmcnt(0)
	v_div_scale_f32 v45, s[28:29], v44, v44, s22
	v_rcp_f32_e32 v61, v45
	v_div_scale_f32 v68, vcc, s22, v44, s22
	v_fma_f32 v69, -v45, v61, 1.0
	v_fmac_f32_e32 v61, v69, v61
	v_mul_f32_e32 v69, v68, v61
	v_fma_f32 v70, -v45, v69, v68
	v_fmac_f32_e32 v69, v70, v61
	v_fma_f32 v45, -v45, v69, v68
	v_div_fmas_f32 v45, v45, v61, v69
	v_div_fixup_f32 v45, v45, v44, s22
	v_cmp_lt_f32_e32 vcc, 0, v44
	s_nop 1
	v_cndmask_b32_e32 v45, 0, v45, vcc
	s_waitcnt lgkmcnt(0)
	v_mul_f32_e32 v61, v62, v45
	v_mul_f32_e32 v62, v45, v63
	v_mul_f32_e32 v43, v45, v43
	v_rndne_f32_e32 v62, v62
	v_mul_f32_e32 v42, v42, v45
	v_mul_f32_e32 v63, v45, v64
	v_rndne_f32_e32 v61, v61
	v_rndne_f32_e32 v43, v43
	v_cvt_i32_f32_e32 v62, v62
	v_rndne_f32_e32 v42, v42
	v_rndne_f32_e32 v63, v63
	v_cvt_i32_f32_e32 v61, v61
	v_cvt_i32_f32_e32 v43, v43
	v_cvt_i32_f32_e32 v42, v42
	v_cvt_i32_f32_e32 v63, v63
	v_med3_i32 v62, v62, s23, v53
	v_med3_i32 v61, v61, s23, v53
	v_med3_i32 v43, v43, s23, v53
	v_lshlrev_b32_e32 v62, 8, v62
	v_mul_f32_e32 v64, v45, v66
	v_med3_i32 v42, v42, s23, v53
	v_lshlrev_b32_e32 v43, 8, v43
	v_perm_b32 v61, v62, v61, s24
	v_med3_i32 v62, v63, s23, v53
	v_mul_f32_e32 v63, v45, v65
	v_perm_b32 v42, v43, v42, s24
	v_rndne_f32_e32 v43, v64
	v_rndne_f32_e32 v63, v63
	v_mul_f32_e32 v45, v45, v67
	v_cvt_i32_f32_e32 v43, v43
	v_cvt_i32_f32_e32 v63, v63
	v_rndne_f32_e32 v45, v45
	v_cvt_i32_f32_e32 v45, v45
	v_med3_i32 v43, v43, s23, v53
	v_lshlrev_b32_e32 v62, 16, v62
	v_med3_i32 v63, v63, s23, v53
	v_and_b32_e32 v62, 0xff0000, v62
	v_lshlrev_b32_e32 v43, 16, v43
	v_med3_i32 v45, v45, s23, v53
	v_lshlrev_b32_e32 v63, 24, v63
	v_and_b32_e32 v43, 0xff0000, v43
	v_or3_b32 v62, v42, v62, v63
	v_lshlrev_b32_e32 v42, 24, v45
	v_or3_b32 v63, v61, v43, v42
	v_add_u32_e32 v42, s6, v47
	v_ashrrev_i32_e32 v43, 31, v42
	v_lshlrev_b64 v[64:65], 11, v[42:43]
	v_lshl_add_u64 v[64:65], v[38:39], 0, v[64:65]
	global_store_dwordx2 v[64:65], v[62:63], off
	s_and_saveexec_b64 s[6:7], s[12:13]
	s_cbranch_execz .LBB0_136
	v_lshl_add_u64 v[62:63], v[42:43], 2, s[8:9]
	v_mul_f32_e32 v43, 0x3c010204, v44
	global_store_dword v[62:63], v43, off
; #define LAS __attribute__((address_space(3)))
; __device__ __forceinline__ float ld_agent(const float* p) { return __hip_atomic_load(p, __ATOMIC_RELAXED, __HIP_MEMORY_SCOPE_AGENT); }
; template <int MODE>
; __device__ __forceinline__ void quant_finish(const float (&r)[32], int K, int N, unsigned char* W8, const float* colmax, float* swinv, LAS float* scr, int item, int lane) {
;     ...
;     for (int j = 0; j < 4; ++j) { const int n = (lane >> 3) + 8 * j; const LAS float* sp = scr + (8 * c) * 33 + n;
;         const float cm = ld_agent(colmax + n0 + n), sc = cm > 0.f ? 127.f / cm : 0.f;
;         unsigned w0 = 0u, w1 = 0u;
; #pragma unroll
;         for (int e = 0; e < 4; ++e) { int q0 = (int)rintf(sp[e * 33] * sc), q1 = (int)rintf(sp[(e + 4) * 33] * sc);
;             q0 = q0 < -127 ? -127 : (q0 > 127 ? 127 : q0); q1 = q1 < -127 ? -127 : (q1 > 127 ? 127 : q1);
;             w0 |= ((unsigned)q0 & 0xffu) << (8 * e); w1 |= ((unsigned)q1 & 0xffu) << (8 * e); }
;         u32x2 o; o.x = w0; o.y = w1;
;         *(u32x2*)(W8 + (size_t)(d0 + n) * K + k0 + 8 * c) = o;
;         if (kb == 0 && c == 0) swinv[d0 + n] = cm * (1.f / 127.f); }
.LBB0_136:
	s_or_b64 exec, exec, s[6:7]
	v_mov_b32_e32 v43, v200
	ds_read2_b32 v[62:63], v48 offset0:8 offset1:41
	ds_read2_b32 v[64:65], v48 offset0:140 offset1:173
	ds_read2_b32 v[66:67], v48 offset0:74 offset1:107
	ds_read2_b32 v[68:69], v48 offset0:206 offset1:239
	v_add_u32_e32 v44, 8, v42
	v_ashrrev_i32_e32 v45, 31, v44
	v_lshlrev_b64 v[70:71], 11, v[44:45]
	v_div_scale_f32 v61, s[6:7], v43, v43, s22
	v_rcp_f32_e32 v72, v61
	v_div_scale_f32 v73, vcc, s22, v43, s22
	v_fma_f32 v74, -v61, v72, 1.0
	v_fmac_f32_e32 v72, v74, v72
	v_mul_f32_e32 v74, v73, v72
	v_fma_f32 v75, -v61, v74, v73
	v_fmac_f32_e32 v74, v75, v72
	v_fma_f32 v61, -v61, v74, v73
	v_div_fmas_f32 v61, v61, v72, v74
	v_div_fixup_f32 v61, v61, v43, s22
	v_cmp_lt_f32_e32 vcc, 0, v43
	s_nop 1
	v_cndmask_b32_e32 v61, 0, v61, vcc
	s_waitcnt lgkmcnt(3)
	v_mul_f32_e32 v63, v61, v63
	s_waitcnt lgkmcnt(2)
	v_mul_f32_e32 v65, v61, v65
	s_waitcnt lgkmcnt(1)
	v_mul_f32_e32 v66, v61, v66
	s_waitcnt lgkmcnt(0)
	v_mul_f32_e32 v68, v61, v68
	v_mul_f32_e32 v62, v62, v61
	v_mul_f32_e32 v64, v64, v61
	v_mul_f32_e32 v67, v61, v67
	v_mul_f32_e32 v61, v61, v69
	v_rndne_f32_e32 v63, v63
	v_rndne_f32_e32 v65, v65
	v_rndne_f32_e32 v66, v66
	v_rndne_f32_e32 v68, v68
	v_rndne_f32_e32 v62, v62
	v_rndne_f32_e32 v64, v64
	v_rndne_f32_e32 v67, v67
	v_rndne_f32_e32 v61, v61
	v_cvt_i32_f32_e32 v63, v63
	v_cvt_i32_f32_e32 v65, v65
	v_cvt_i32_f32_e32 v66, v66
	v_cvt_i32_f32_e32 v68, v68
	v_cvt_i32_f32_e32 v62, v62
	v_cvt_i32_f32_e32 v64, v64
	v_cvt_i32_f32_e32 v67, v67
	v_cvt_i32_f32_e32 v61, v61
	v_med3_i32 v63, v63, s23, v53
	v_med3_i32 v65, v65, s23, v53
	v_med3_i32 v66, v66, s23, v53
	v_med3_i32 v68, v68, s23, v53
	v_med3_i32 v62, v62, s23, v53
	v_med3_i32 v64, v64, s23, v53
	v_med3_i32 v67, v67, s23, v53
	v_med3_i32 v61, v61, s23, v53
	v_lshlrev_b32_e32 v63, 8, v63
	v_lshlrev_b32_e32 v65, 8, v65
	v_lshlrev_b32_e32 v66, 16, v66
	v_lshlrev_b32_e32 v68, 16, v68
	v_lshlrev_b32_e32 v67, 24, v67
	v_lshlrev_b32_e32 v61, 24, v61
	v_perm_b32 v62, v63, v62, s24
	v_perm_b32 v63, v65, v64, s24
	v_and_b32_e32 v64, 0xff0000, v66
	v_and_b32_e32 v65, 0xff0000, v68
	v_or3_b32 v62, v62, v64, v67
	v_or3_b32 v63, v63, v65, v61
	v_lshl_add_u64 v[64:65], v[38:39], 0, v[70:71]
	global_store_dwordx2 v[64:65], v[62:63], off
	s_and_saveexec_b64 s[6:7], s[12:13]
	s_cbranch_execz .LBB0_138
	v_lshl_add_u64 v[44:45], v[44:45], 2, s[8:9]
	v_mul_f32_e32 v43, 0x3c010204, v43
	global_store_dword v[44:45], v43, off
.LBB0_138:
	s_or_b64 exec, exec, s[6:7]
	v_mov_b32_e32 v43, v201
	ds_read2_b32 v[62:63], v48 offset0:16 offset1:49
	ds_read2_b32 v[64:65], v48 offset0:148 offset1:181
	ds_read2_b32 v[66:67], v48 offset0:82 offset1:115
	ds_read2_b32 v[68:69], v48 offset0:214 offset1:247
	v_add_u32_e32 v44, 16, v42
	v_ashrrev_i32_e32 v45, 31, v44
	v_lshlrev_b64 v[70:71], 11, v[44:45]
	v_div_scale_f32 v61, s[6:7], v43, v43, s22
	v_rcp_f32_e32 v72, v61
	v_div_scale_f32 v73, vcc, s22, v43, s22
	v_fma_f32 v74, -v61, v72, 1.0
	v_fmac_f32_e32 v72, v74, v72
	v_mul_f32_e32 v74, v73, v72
	v_fma_f32 v75, -v61, v74, v73
	v_fmac_f32_e32 v74, v75, v72
	v_fma_f32 v61, -v61, v74, v73
	v_div_fmas_f32 v61, v61, v72, v74
	v_div_fixup_f32 v61, v61, v43, s22
	v_cmp_lt_f32_e32 vcc, 0, v43
	s_nop 1
	v_cndmask_b32_e32 v61, 0, v61, vcc
	s_waitcnt lgkmcnt(3)
	v_mul_f32_e32 v63, v61, v63
	s_waitcnt lgkmcnt(2)
	v_mul_f32_e32 v65, v61, v65
	s_waitcnt lgkmcnt(1)
	v_mul_f32_e32 v66, v61, v66
	s_waitcnt lgkmcnt(0)
	v_mul_f32_e32 v68, v61, v68
	v_mul_f32_e32 v62, v62, v61
	v_mul_f32_e32 v64, v64, v61
	v_mul_f32_e32 v67, v61, v67
	v_mul_f32_e32 v61, v61, v69
	v_rndne_f32_e32 v63, v63
	v_rndne_f32_e32 v65, v65
	v_rndne_f32_e32 v66, v66
	v_rndne_f32_e32 v68, v68
	v_rndne_f32_e32 v62, v62
	v_rndne_f32_e32 v64, v64
	v_rndne_f32_e32 v67, v67
	v_rndne_f32_e32 v61, v61
	v_cvt_i32_f32_e32 v63, v63
	v_cvt_i32_f32_e32 v65, v65
	v_cvt_i32_f32_e32 v66, v66
	v_cvt_i32_f32_e32 v68, v68
	v_cvt_i32_f32_e32 v62, v62
	v_cvt_i32_f32_e32 v64, v64
	v_cvt_i32_f32_e32 v67, v67
	v_cvt_i32_f32_e32 v61, v61
	v_med3_i32 v63, v63, s23, v53
	v_med3_i32 v65, v65, s23, v53
	v_med3_i32 v66, v66, s23, v53
	v_med3_i32 v68, v68, s23, v53
	v_med3_i32 v62, v62, s23, v53
	v_med3_i32 v64, v64, s23, v53
	v_med3_i32 v67, v67, s23, v53
	v_med3_i32 v61, v61, s23, v53
	v_lshlrev_b32_e32 v63, 8, v63
	v_lshlrev_b32_e32 v65, 8, v65
	v_lshlrev_b32_e32 v66, 16, v66
	v_lshlrev_b32_e32 v68, 16, v68
	v_lshlrev_b32_e32 v67, 24, v67
	v_lshlrev_b32_e32 v61, 24, v61
	v_perm_b32 v62, v63, v62, s24
	v_perm_b32 v63, v65, v64, s24
	v_and_b32_e32 v64, 0xff0000, v66
	v_and_b32_e32 v65, 0xff0000, v68
	v_or3_b32 v62, v62, v64, v67
	v_or3_b32 v63, v63, v65, v61
	v_lshl_add_u64 v[64:65], v[38:39], 0, v[70:71]
	global_store_dwordx2 v[64:65], v[62:63], off
	s_and_saveexec_b64 s[6:7], s[12:13]
	s_cbranch_execz .LBB0_140
	v_lshl_add_u64 v[44:45], v[44:45], 2, s[8:9]
	v_mul_f32_e32 v43, 0x3c010204, v43
	global_store_dword v[44:45], v43, off
; #define LAS __attribute__((address_space(3)))
; __device__ __forceinline__ float ld_agent(const float* p) { return __hip_atomic_load(p, __ATOMIC_RELAXED, __HIP_MEMORY_SCOPE_AGENT); }
; template <int MODE>
; __device__ __forceinline__ void quant_finish(const float (&r)[32], int K, int N, unsigned char* W8, const float* colmax, float* swinv, LAS float* scr, int item, int lane) {
;     ...
;     for (int j = 0; j < 4; ++j) { const int n = (lane >> 3) + 8 * j; const LAS float* sp = scr + (8 * c) * 33 + n;
;         const float cm = ld_agent(colmax + n0 + n), sc = cm > 0.f ? 127.f / cm : 0.f;
;         unsigned w0 = 0u, w1 = 0u;
; #pragma unroll
;         for (int e = 0; e < 4; ++e) { int q0 = (int)rintf(sp[e * 33] * sc), q1 = (int)rintf(sp[(e + 4) * 33] * sc);
;             q0 = q0 < -127 ? -127 : (q0 > 127 ? 127 : q0); q1 = q1 < -127 ? -127 : (q1 > 127 ? 127 : q1);
;             w0 |= ((unsigned)q0 & 0xffu) << (8 * e); w1 |= ((unsigned)q1 & 0xffu) << (8 * e); }
;         u32x2 o; o.x = w0; o.y = w1;
;         *(u32x2*)(W8 + (size_t)(d0 + n) * K + k0 + 8 * c) = o;
;         if (kb == 0 && c == 0) swinv[d0 + n] = cm * (1.f / 127.f); }
;     asm volatile("s_waitcnt lgkmcnt(0)" ::: "memory");
; template <int MODE, bool GAIN>
; __device__ __forceinline__ void quant_loop2(const float* W, int K, int N, unsigned char* W8, const float* gain, const float* colmax, float* swinv, LAS float* scr, int first, int n, int stride, int lane) {
;     for (int it = first; it < n; it += 2 * stride) { const int itB = it + stride; float ra[32], rb[32];
;         item_loads<MODE, GAIN>(W, N, gain, it, lane, ra); if (itB < n) item_loads<MODE, GAIN>(W, N, gain, itB, lane, rb);
;         quant_finish<MODE>(ra, K, N, W8, colmax, swinv, scr, it, lane); if (itB < n) quant_finish<MODE>(rb, K, N, W8, colmax, swinv, scr, itB, lane); }
.LBB0_140:
	s_or_b64 exec, exec, s[6:7]
	v_mov_b32_e32 v43, v202
	v_add_u32_e32 v40, 24, v42
	ds_read2_b32 v[44:45], v48 offset0:24 offset1:57
	ds_read2_b32 v[62:63], v48 offset0:156 offset1:189
	ds_read2_b32 v[64:65], v48 offset0:90 offset1:123
	ds_read2_b32 v[66:67], v48 offset0:222 offset1:255
	v_ashrrev_i32_e32 v41, 31, v40
	v_lshlrev_b64 v[68:69], 11, v[40:41]
	v_lshl_add_u64 v[38:39], v[38:39], 0, v[68:69]
	v_div_scale_f32 v42, s[6:7], v43, v43, s22
	v_rcp_f32_e32 v61, v42
	v_div_scale_f32 v70, vcc, s22, v43, s22
	v_fma_f32 v71, -v42, v61, 1.0
	v_fmac_f32_e32 v61, v71, v61
	v_mul_f32_e32 v71, v70, v61
	v_fma_f32 v72, -v42, v71, v70
	v_fmac_f32_e32 v71, v72, v61
	v_fma_f32 v42, -v42, v71, v70
	v_div_fmas_f32 v42, v42, v61, v71
	v_div_fixup_f32 v42, v42, v43, s22
	v_cmp_lt_f32_e32 vcc, 0, v43
	s_nop 1
	v_cndmask_b32_e32 v42, 0, v42, vcc
	s_waitcnt lgkmcnt(2)
	v_mul_f32_e32 v61, v62, v42
	v_mul_f32_e32 v45, v42, v45
	v_mul_f32_e32 v62, v42, v63
	s_waitcnt lgkmcnt(1)
	v_mul_f32_e32 v63, v42, v64
	s_waitcnt lgkmcnt(0)
	v_mul_f32_e32 v64, v42, v66
	v_mul_f32_e32 v44, v44, v42
	v_mul_f32_e32 v65, v42, v65
	v_mul_f32_e32 v42, v42, v67
	v_rndne_f32_e32 v45, v45
	v_rndne_f32_e32 v62, v62
	v_rndne_f32_e32 v63, v63
	v_rndne_f32_e32 v64, v64
	v_rndne_f32_e32 v44, v44
	v_rndne_f32_e32 v61, v61
	v_rndne_f32_e32 v65, v65
	v_rndne_f32_e32 v42, v42
	v_cvt_i32_f32_e32 v45, v45
	v_cvt_i32_f32_e32 v62, v62
	v_cvt_i32_f32_e32 v63, v63
	v_cvt_i32_f32_e32 v64, v64
	v_cvt_i32_f32_e32 v44, v44
	v_cvt_i32_f32_e32 v61, v61
	v_cvt_i32_f32_e32 v65, v65
	v_cvt_i32_f32_e32 v42, v42
	v_med3_i32 v45, v45, s23, v53
	v_med3_i32 v62, v62, s23, v53
	v_med3_i32 v63, v63, s23, v53
	v_med3_i32 v64, v64, s23, v53
	v_med3_i32 v44, v44, s23, v53
	v_med3_i32 v61, v61, s23, v53
	v_med3_i32 v65, v65, s23, v53
	v_med3_i32 v42, v42, s23, v53
	v_lshlrev_b32_e32 v45, 8, v45
	v_lshlrev_b32_e32 v62, 8, v62
	v_lshlrev_b32_e32 v63, 16, v63
	v_lshlrev_b32_e32 v64, 16, v64
	v_lshlrev_b32_e32 v65, 24, v65
	v_lshlrev_b32_e32 v42, 24, v42
	v_perm_b32 v44, v45, v44, s24
	v_perm_b32 v45, v62, v61, s24
	v_and_b32_e32 v61, 0xff0000, v63
	v_and_b32_e32 v62, 0xff0000, v64
	v_or3_b32 v44, v44, v61, v65
	v_or3_b32 v45, v45, v62, v42
	global_store_dwordx2 v[38:39], v[44:45], off
	s_and_saveexec_b64 s[6:7], s[12:13]
	s_cbranch_execz .LBB0_142
	v_lshl_add_u64 v[38:39], v[40:41], 2, s[8:9]
	v_mul_f32_e32 v40, 0x3c010204, v43
	global_store_dword v[38:39], v40, off
.LBB0_142:
	s_or_b64 exec, exec, s[6:7]
	s_waitcnt lgkmcnt(0)
	s_andn2_b64 vcc, exec, s[2:3]
	s_cbranch_vccnz .LBB0_131
	s_lshr_b32 s2, s27, 31
	s_ashr_i32 s3, s27, 7
	s_add_i32 s6, s3, s2
	s_mul_i32 s2, s6, 0x110
	s_sub_i32 s2, s26, s2
	s_lshl_b32 s2, s2, 5
	ds_write2_b32 v52, v35, v34 offset1:66
	ds_write2_b32 v52, v33, v32 offset0:132 offset1:198
	ds_write2_b32 v54, v31, v30 offset0:8 offset1:74
	ds_write2_b32 v54, v29, v28 offset0:140 offset1:206
	ds_write2_b32 v55, v27, v26 offset0:16 offset1:82
	ds_write2_b32 v55, v25, v24 offset0:148 offset1:214
	ds_write2_b32 v56, v23, v22 offset0:24 offset1:90
	ds_write2_b32 v56, v21, v20 offset0:156 offset1:222
	ds_write2_b32 v57, v19, v18 offset0:32 offset1:98
	ds_write2_b32 v57, v17, v16 offset0:164 offset1:230
	ds_write2_b32 v58, v15, v14 offset0:40 offset1:106
	ds_write2_b32 v58, v13, v12 offset0:172 offset1:238
	ds_write2_b32 v59, v11, v10 offset0:48 offset1:114
	ds_write2_b32 v59, v9, v8 offset0:180 offset1:246
	ds_write2_b32 v60, v7, v6 offset0:56 offset1:122
	ds_write2_b32 v60, v37, v36 offset0:188 offset1:254
	s_ashr_i32 s3, s2, 31
	s_waitcnt lgkmcnt(0)
	v_lshl_add_u64 v[40:41], s[2:3], 2, v[4:5]
	global_load_dword v44, v[40:41], off sc1
	global_load_dword v200, v[40:41], off offset:32 sc1
	global_load_dword v201, v[40:41], off offset:64 sc1
	global_load_dword v202, v[40:41], off offset:96 sc1
	ds_read2_b32 v[54:55], v48 offset1:33
	ds_read2_b32 v[56:57], v48 offset0:132 offset1:165
	ds_read2_b32 v[58:59], v48 offset0:66 offset1:99
	ds_read2_b32 v[60:61], v48 offset0:198 offset1:231
	s_lshl_b32 s6, s6, 6
	s_addk_i32 s26, 0x10f
	s_ashr_i32 s7, s6, 31
	v_or_b32_e32 v42, s2, v47
	s_cmpk_lt_u32 s26, 0x21f
	v_ashrrev_i32_e32 v43, 31, v42
	v_lshl_add_u64 v[38:39], v[2:3], 0, s[6:7]
	s_cselect_b64 s[6:7], -1, 0
	v_lshlrev_b64 v[62:63], 11, v[42:43]
	s_and_b64 s[6:7], s[0:1], s[6:7]
	s_waitcnt vmcnt(0)
	v_div_scale_f32 v45, s[12:13], v44, v44, s22
	v_rcp_f32_e32 v64, v45
	v_div_scale_f32 v65, vcc, s22, v44, s22
	v_fma_f32 v66, -v45, v64, 1.0
	v_fmac_f32_e32 v64, v66, v64
	v_mul_f32_e32 v66, v65, v64
	v_fma_f32 v67, -v45, v66, v65
	v_fmac_f32_e32 v66, v67, v64
	v_fma_f32 v45, -v45, v66, v65
	v_div_fmas_f32 v45, v45, v64, v66
	v_div_fixup_f32 v45, v45, v44, s22
	v_cmp_lt_f32_e32 vcc, 0, v44
	s_nop 1
	v_cndmask_b32_e32 v45, 0, v45, vcc
	s_waitcnt lgkmcnt(3)
	v_mul_f32_e32 v55, v45, v55
	s_waitcnt lgkmcnt(2)
	v_mul_f32_e32 v57, v45, v57
	s_waitcnt lgkmcnt(1)
	v_mul_f32_e32 v58, v45, v58
	s_waitcnt lgkmcnt(0)
	v_mul_f32_e32 v60, v45, v60
	v_mul_f32_e32 v54, v54, v45
	v_mul_f32_e32 v56, v56, v45
	v_mul_f32_e32 v59, v45, v59
	v_mul_f32_e32 v45, v45, v61
	v_rndne_f32_e32 v55, v55
	v_rndne_f32_e32 v57, v57
	v_rndne_f32_e32 v58, v58
	v_rndne_f32_e32 v60, v60
	v_rndne_f32_e32 v54, v54
	v_rndne_f32_e32 v56, v56
	v_rndne_f32_e32 v59, v59
	v_rndne_f32_e32 v45, v45
	v_cvt_i32_f32_e32 v55, v55
	v_cvt_i32_f32_e32 v57, v57
	v_cvt_i32_f32_e32 v58, v58
	v_cvt_i32_f32_e32 v60, v60
	v_cvt_i32_f32_e32 v54, v54
	v_cvt_i32_f32_e32 v56, v56
	v_cvt_i32_f32_e32 v59, v59
	v_cvt_i32_f32_e32 v45, v45
	v_med3_i32 v55, v55, s23, v53
	v_med3_i32 v57, v57, s23, v53
	v_med3_i32 v58, v58, s23, v53
	v_med3_i32 v60, v60, s23, v53
	v_med3_i32 v54, v54, s23, v53
	v_med3_i32 v56, v56, s23, v53
	v_med3_i32 v59, v59, s23, v53
	v_med3_i32 v45, v45, s23, v53
	v_lshlrev_b32_e32 v55, 8, v55
	v_lshlrev_b32_e32 v57, 8, v57
	v_lshlrev_b32_e32 v58, 16, v58
	v_lshlrev_b32_e32 v60, 16, v60
	v_lshlrev_b32_e32 v59, 24, v59
	v_lshlrev_b32_e32 v45, 24, v45
	v_perm_b32 v54, v55, v54, s24
	v_perm_b32 v55, v57, v56, s24
	v_and_b32_e32 v56, 0xff0000, v58
	v_and_b32_e32 v57, 0xff0000, v60
	v_or3_b32 v54, v54, v56, v59
	v_or3_b32 v55, v55, v57, v45
	v_lshl_add_u64 v[56:57], v[38:39], 0, v[62:63]
	global_store_dwordx2 v[56:57], v[54:55], off
	s_and_saveexec_b64 s[12:13], s[6:7]
	s_cbranch_execz .LBB0_145
	v_lshl_add_u64 v[42:43], v[42:43], 2, s[8:9]
	v_mul_f32_e32 v44, 0x3c010204, v44
	global_store_dword v[42:43], v44, off
; #define LAS __attribute__((address_space(3)))
; __device__ __forceinline__ float ld_agent(const float* p) { return __hip_atomic_load(p, __ATOMIC_RELAXED, __HIP_MEMORY_SCOPE_AGENT); }
; template <int MODE>
; __device__ __forceinline__ void quant_finish(const float (&r)[32], int K, int N, unsigned char* W8, const float* colmax, float* swinv, LAS float* scr, int item, int lane) {
;     ...
;     for (int j = 0; j < 4; ++j) { const int n = (lane >> 3) + 8 * j; const LAS float* sp = scr + (8 * c) * 33 + n;
;         const float cm = ld_agent(colmax + n0 + n), sc = cm > 0.f ? 127.f / cm : 0.f;
;         unsigned w0 = 0u, w1 = 0u;
; #pragma unroll
;         for (int e = 0; e < 4; ++e) { int q0 = (int)rintf(sp[e * 33] * sc), q1 = (int)rintf(sp[(e + 4) * 33] * sc);
;             q0 = q0 < -127 ? -127 : (q0 > 127 ? 127 : q0); q1 = q1 < -127 ? -127 : (q1 > 127 ? 127 : q1);
;             w0 |= ((unsigned)q0 & 0xffu) << (8 * e); w1 |= ((unsigned)q1 & 0xffu) << (8 * e); }
;         u32x2 o; o.x = w0; o.y = w1;
;         *(u32x2*)(W8 + (size_t)(d0 + n) * K + k0 + 8 * c) = o;
;         if (kb == 0 && c == 0) swinv[d0 + n] = cm * (1.f / 127.f); }
.LBB0_145:
	s_or_b64 exec, exec, s[12:13]
	v_mov_b32_e32 v44, v200
	ds_read2_b32 v[54:55], v48 offset0:8 offset1:41
	ds_read2_b32 v[56:57], v48 offset0:140 offset1:173
	ds_read2_b32 v[58:59], v48 offset0:74 offset1:107
	ds_read2_b32 v[60:61], v48 offset0:206 offset1:239
	v_or_b32_e32 v42, s2, v49
	v_ashrrev_i32_e32 v43, 31, v42
	v_lshlrev_b64 v[62:63], 11, v[42:43]
	v_div_scale_f32 v45, s[12:13], v44, v44, s22
	v_rcp_f32_e32 v64, v45
	v_div_scale_f32 v65, vcc, s22, v44, s22
	v_fma_f32 v66, -v45, v64, 1.0
	v_fmac_f32_e32 v64, v66, v64
	v_mul_f32_e32 v66, v65, v64
	v_fma_f32 v67, -v45, v66, v65
	v_fmac_f32_e32 v66, v67, v64
	v_fma_f32 v45, -v45, v66, v65
	v_div_fmas_f32 v45, v45, v64, v66
	v_div_fixup_f32 v45, v45, v44, s22
	v_cmp_lt_f32_e32 vcc, 0, v44
	s_nop 1
	v_cndmask_b32_e32 v45, 0, v45, vcc
	s_waitcnt lgkmcnt(3)
	v_mul_f32_e32 v55, v45, v55
	s_waitcnt lgkmcnt(2)
	v_mul_f32_e32 v57, v45, v57
	s_waitcnt lgkmcnt(1)
	v_mul_f32_e32 v58, v45, v58
	s_waitcnt lgkmcnt(0)
	v_mul_f32_e32 v60, v45, v60
	v_mul_f32_e32 v54, v54, v45
	v_mul_f32_e32 v56, v56, v45
	v_mul_f32_e32 v59, v45, v59
	v_mul_f32_e32 v45, v45, v61
	v_rndne_f32_e32 v55, v55
	v_rndne_f32_e32 v57, v57
	v_rndne_f32_e32 v58, v58
	v_rndne_f32_e32 v60, v60
	v_rndne_f32_e32 v54, v54
	v_rndne_f32_e32 v56, v56
	v_rndne_f32_e32 v59, v59
	v_rndne_f32_e32 v45, v45
	v_cvt_i32_f32_e32 v55, v55
	v_cvt_i32_f32_e32 v57, v57
	v_cvt_i32_f32_e32 v58, v58
	v_cvt_i32_f32_e32 v60, v60
	v_cvt_i32_f32_e32 v54, v54
	v_cvt_i32_f32_e32 v56, v56
	v_cvt_i32_f32_e32 v59, v59
	v_cvt_i32_f32_e32 v45, v45
	v_med3_i32 v55, v55, s23, v53
	v_med3_i32 v57, v57, s23, v53
	v_med3_i32 v58, v58, s23, v53
	v_med3_i32 v60, v60, s23, v53
	v_med3_i32 v54, v54, s23, v53
	v_med3_i32 v56, v56, s23, v53
	v_med3_i32 v59, v59, s23, v53
	v_med3_i32 v45, v45, s23, v53
	v_lshlrev_b32_e32 v55, 8, v55
	v_lshlrev_b32_e32 v57, 8, v57
	v_lshlrev_b32_e32 v58, 16, v58
	v_lshlrev_b32_e32 v60, 16, v60
	v_lshlrev_b32_e32 v59, 24, v59
	v_lshlrev_b32_e32 v45, 24, v45
	v_perm_b32 v54, v55, v54, s24
	v_perm_b32 v55, v57, v56, s24
	v_and_b32_e32 v56, 0xff0000, v58
	v_and_b32_e32 v57, 0xff0000, v60
	v_or3_b32 v54, v54, v56, v59
	v_or3_b32 v55, v55, v57, v45
	v_lshl_add_u64 v[56:57], v[38:39], 0, v[62:63]
	global_store_dwordx2 v[56:57], v[54:55], off
	s_and_saveexec_b64 s[12:13], s[6:7]
	s_cbranch_execz .LBB0_147
	v_lshl_add_u64 v[42:43], v[42:43], 2, s[8:9]
	v_mul_f32_e32 v44, 0x3c010204, v44
	global_store_dword v[42:43], v44, off
.LBB0_147:
	s_or_b64 exec, exec, s[12:13]
	v_mov_b32_e32 v44, v201
	ds_read2_b32 v[54:55], v48 offset0:16 offset1:49
	ds_read2_b32 v[56:57], v48 offset0:148 offset1:181
	ds_read2_b32 v[58:59], v48 offset0:82 offset1:115
	ds_read2_b32 v[60:61], v48 offset0:214 offset1:247
	v_or_b32_e32 v42, s2, v50
	v_ashrrev_i32_e32 v43, 31, v42
	v_lshlrev_b64 v[62:63], 11, v[42:43]
	v_div_scale_f32 v45, s[12:13], v44, v44, s22
	v_rcp_f32_e32 v64, v45
	v_div_scale_f32 v65, vcc, s22, v44, s22
	v_fma_f32 v66, -v45, v64, 1.0
	v_fmac_f32_e32 v64, v66, v64
	v_mul_f32_e32 v66, v65, v64
	v_fma_f32 v67, -v45, v66, v65
	v_fmac_f32_e32 v66, v67, v64
	v_fma_f32 v45, -v45, v66, v65
	v_div_fmas_f32 v45, v45, v64, v66
	v_div_fixup_f32 v45, v45, v44, s22
	v_cmp_lt_f32_e32 vcc, 0, v44
	s_nop 1
	v_cndmask_b32_e32 v45, 0, v45, vcc
	s_waitcnt lgkmcnt(3)
	v_mul_f32_e32 v55, v45, v55
	s_waitcnt lgkmcnt(2)
	v_mul_f32_e32 v57, v45, v57
	s_waitcnt lgkmcnt(1)
	v_mul_f32_e32 v58, v45, v58
	s_waitcnt lgkmcnt(0)
	v_mul_f32_e32 v60, v45, v60
	v_mul_f32_e32 v54, v54, v45
	v_mul_f32_e32 v56, v56, v45
	v_mul_f32_e32 v59, v45, v59
	v_mul_f32_e32 v45, v45, v61
	v_rndne_f32_e32 v55, v55
	v_rndne_f32_e32 v57, v57
	v_rndne_f32_e32 v58, v58
	v_rndne_f32_e32 v60, v60
	v_rndne_f32_e32 v54, v54
	v_rndne_f32_e32 v56, v56
	v_rndne_f32_e32 v59, v59
	v_rndne_f32_e32 v45, v45
	v_cvt_i32_f32_e32 v55, v55
	v_cvt_i32_f32_e32 v57, v57
	v_cvt_i32_f32_e32 v58, v58
	v_cvt_i32_f32_e32 v60, v60
	v_cvt_i32_f32_e32 v54, v54
	v_cvt_i32_f32_e32 v56, v56
	v_cvt_i32_f32_e32 v59, v59
	v_cvt_i32_f32_e32 v45, v45
	v_med3_i32 v55, v55, s23, v53
	v_med3_i32 v57, v57, s23, v53
	v_med3_i32 v58, v58, s23, v53
	v_med3_i32 v60, v60, s23, v53
	v_med3_i32 v54, v54, s23, v53
	v_med3_i32 v56, v56, s23, v53
	v_med3_i32 v59, v59, s23, v53
	v_med3_i32 v45, v45, s23, v53
	v_lshlrev_b32_e32 v55, 8, v55
	v_lshlrev_b32_e32 v57, 8, v57
	v_lshlrev_b32_e32 v58, 16, v58
	v_lshlrev_b32_e32 v60, 16, v60
	v_lshlrev_b32_e32 v59, 24, v59
	v_lshlrev_b32_e32 v45, 24, v45
	v_perm_b32 v54, v55, v54, s24
	v_perm_b32 v55, v57, v56, s24
	v_and_b32_e32 v56, 0xff0000, v58
	v_and_b32_e32 v57, 0xff0000, v60
	v_or3_b32 v54, v54, v56, v59
	v_or3_b32 v55, v55, v57, v45
	v_lshl_add_u64 v[56:57], v[38:39], 0, v[62:63]
	global_store_dwordx2 v[56:57], v[54:55], off
	s_and_saveexec_b64 s[12:13], s[6:7]
	s_cbranch_execz .LBB0_149
	v_lshl_add_u64 v[42:43], v[42:43], 2, s[8:9]
	v_mul_f32_e32 v44, 0x3c010204, v44
	global_store_dword v[42:43], v44, off
; #define LAS __attribute__((address_space(3)))
; __device__ __forceinline__ float ld_agent(const float* p) { return __hip_atomic_load(p, __ATOMIC_RELAXED, __HIP_MEMORY_SCOPE_AGENT); }
; template <int MODE>
; __device__ __forceinline__ void quant_finish(const float (&r)[32], int K, int N, unsigned char* W8, const float* colmax, float* swinv, LAS float* scr, int item, int lane) {
;     ...
;     for (int j = 0; j < 4; ++j) { const int n = (lane >> 3) + 8 * j; const LAS float* sp = scr + (8 * c) * 33 + n;
;         const float cm = ld_agent(colmax + n0 + n), sc = cm > 0.f ? 127.f / cm : 0.f;
;         unsigned w0 = 0u, w1 = 0u;
; #pragma unroll
;         for (int e = 0; e < 4; ++e) { int q0 = (int)rintf(sp[e * 33] * sc), q1 = (int)rintf(sp[(e + 4) * 33] * sc);
;             q0 = q0 < -127 ? -127 : (q0 > 127 ? 127 : q0); q1 = q1 < -127 ? -127 : (q1 > 127 ? 127 : q1);
;             w0 |= ((unsigned)q0 & 0xffu) << (8 * e); w1 |= ((unsigned)q1 & 0xffu) << (8 * e); }
;         u32x2 o; o.x = w0; o.y = w1;
;         *(u32x2*)(W8 + (size_t)(d0 + n) * K + k0 + 8 * c) = o;
;         if (kb == 0 && c == 0) swinv[d0 + n] = cm * (1.f / 127.f); }
.LBB0_149:
	s_or_b64 exec, exec, s[12:13]
	v_mov_b32_e32 v42, v202
	v_or_b32_e32 v40, s2, v51
	ds_read2_b32 v[44:45], v48 offset0:24 offset1:57
	ds_read2_b32 v[54:55], v48 offset0:156 offset1:189
	ds_read2_b32 v[56:57], v48 offset0:90 offset1:123
	ds_read2_b32 v[58:59], v48 offset0:222 offset1:255
	v_ashrrev_i32_e32 v41, 31, v40
	v_lshlrev_b64 v[60:61], 11, v[40:41]
	v_lshl_add_u64 v[38:39], v[38:39], 0, v[60:61]
	v_div_scale_f32 v43, s[2:3], v42, v42, s22
	v_rcp_f32_e32 v62, v43
	v_div_scale_f32 v63, vcc, s22, v42, s22
	v_fma_f32 v64, -v43, v62, 1.0
	v_fmac_f32_e32 v62, v64, v62
	v_mul_f32_e32 v64, v63, v62
	v_fma_f32 v65, -v43, v64, v63
	v_fmac_f32_e32 v64, v65, v62
	v_fma_f32 v43, -v43, v64, v63
	v_div_fmas_f32 v43, v43, v62, v64
	v_div_fixup_f32 v43, v43, v42, s22
	v_cmp_lt_f32_e32 vcc, 0, v42
	s_nop 1
	v_cndmask_b32_e32 v43, 0, v43, vcc
	s_waitcnt lgkmcnt(3)
	v_mul_f32_e32 v45, v43, v45
	s_waitcnt lgkmcnt(2)
	v_mul_f32_e32 v55, v43, v55
	s_waitcnt lgkmcnt(1)
	v_mul_f32_e32 v56, v43, v56
	s_waitcnt lgkmcnt(0)
	v_mul_f32_e32 v58, v43, v58
	v_mul_f32_e32 v44, v44, v43
	v_mul_f32_e32 v54, v54, v43
	v_mul_f32_e32 v57, v43, v57
	v_mul_f32_e32 v43, v43, v59
	v_rndne_f32_e32 v45, v45
	v_rndne_f32_e32 v55, v55
	v_rndne_f32_e32 v56, v56
	v_rndne_f32_e32 v58, v58
	v_rndne_f32_e32 v44, v44
	v_rndne_f32_e32 v54, v54
	v_rndne_f32_e32 v57, v57
	v_rndne_f32_e32 v43, v43
	v_cvt_i32_f32_e32 v45, v45
	v_cvt_i32_f32_e32 v55, v55
	v_cvt_i32_f32_e32 v56, v56
	v_cvt_i32_f32_e32 v58, v58
	v_cvt_i32_f32_e32 v44, v44
	v_cvt_i32_f32_e32 v54, v54
	v_cvt_i32_f32_e32 v57, v57
	v_cvt_i32_f32_e32 v43, v43
	v_med3_i32 v45, v45, s23, v53
	v_med3_i32 v55, v55, s23, v53
	v_med3_i32 v56, v56, s23, v53
	v_med3_i32 v58, v58, s23, v53
	v_med3_i32 v44, v44, s23, v53
	v_med3_i32 v54, v54, s23, v53
	v_med3_i32 v57, v57, s23, v53
	v_med3_i32 v43, v43, s23, v53
	v_lshlrev_b32_e32 v45, 8, v45
	v_lshlrev_b32_e32 v55, 8, v55
	v_lshlrev_b32_e32 v56, 16, v56
	v_lshlrev_b32_e32 v58, 16, v58
	v_lshlrev_b32_e32 v57, 24, v57
	v_lshlrev_b32_e32 v43, 24, v43
	v_perm_b32 v44, v45, v44, s24
	v_perm_b32 v45, v55, v54, s24
	v_and_b32_e32 v54, 0xff0000, v56
	v_and_b32_e32 v55, 0xff0000, v58
	v_or3_b32 v44, v44, v54, v57
	v_or3_b32 v45, v45, v55, v43
	global_store_dwordx2 v[38:39], v[44:45], off
	s_and_saveexec_b64 s[2:3], s[6:7]
	s_cbranch_execz .LBB0_130
	v_lshl_add_u64 v[38:39], v[40:41], 2, s[8:9]
	v_mul_f32_e32 v40, 0x3c010204, v42
	global_store_dword v[38:39], v40, off
	s_branch .LBB0_130
